# XCD-aware tile map for P6 only (cn=(blk>>3)&3, rm=8*(blk&7)+(blk>>5)) on top of v051
# baseline (speedup 1.0000x reference)
.LBB0_395:
	v_mov_b32_e32 v2, v0
	s_bfe_u32 s33, s10, 0x20003
	v_lshlrev_b32_e32 v3, 4, v2
	v_bfe_i32 v2, v2, 27, 1
	v_lshrrev_b32_e32 v2, 22, v2
	v_add_u32_e32 v2, v3, v2
	v_ashrrev_i32_e32 v10, 10, v2
	v_mul_i32_i24_e32 v2, 0x400, v10
	v_sub_u32_e32 v2, v3, v2
	v_add_u32_e32 v4, 0x2000, v3
	v_lshrrev_b32_e32 v3, 4, v2
	v_bitop3_b32 v2, v3, v2, 32 bitop3:0x6c
	v_ashrrev_i32_e32 v5, 31, v2
	v_lshrrev_b32_e32 v5, 26, v5
	v_add_u32_e32 v5, v2, v5
	v_ashrrev_i32_e32 v12, 6, v5
	v_and_b32_e32 v5, 0xc0, v5
	v_sub_u32_e32 v2, v2, v5
	s_waitcnt vmcnt(0)
	v_ashrrev_i16_sdwa v14, v151, sext(v2) dst_sel:DWORD dst_unused:UNUSED_PAD src0_sel:DWORD src1_sel:BYTE_0
	v_ashrrev_i32_e32 v2, 31, v4
	v_lshrrev_b32_e32 v2, 22, v2
	v_add_u32_e32 v2, v4, v2
	v_ashrrev_i32_e32 v11, 10, v2
	v_mul_i32_i24_e32 v2, 0x400, v11
	v_sub_u32_e32 v2, v4, v2
	v_lshrrev_b32_e32 v4, 4, v2
	v_bitop3_b32 v2, v4, v2, 32 bitop3:0x6c
	v_ashrrev_i32_e32 v5, 31, v2
	v_lshrrev_b32_e32 v5, 26, v5
	s_and_b32 s31, s10, 7
	s_lshl_b32 s31, s31, 3
	s_lshr_b32 s98, s10, 5
	s_or_b32 s31, s31, s98
	s_mul_i32 s48, s33, 0x160000
	v_lshlrev_b32_e32 v3, 3, v10
	v_add_u32_e32 v5, v2, v5
	s_add_u32 s22, s44, s48
	v_and_b32_e32 v3, 0xfffff0, v3
	v_lshlrev_b32_e32 v4, 3, v11
	v_ashrrev_i32_e32 v15, 6, v5
	v_and_b32_e32 v5, 0xc0, v5
	s_addc_u32 s23, s45, 0
	s_mul_i32 s50, s31, 0x160000
	v_add_u32_e32 v3, v12, v3
	v_lshlrev_b32_e32 v6, 5, v10
	v_and_b32_e32 v4, 0xfffff0, v4
	v_sub_u32_e32 v2, v2, v5
	s_mul_hi_i32 s49, s31, 0x160000
	s_waitcnt lgkmcnt(0)
	s_add_u32 s26, s14, s50
	v_readfirstlane_b32 s28, v0
	v_and_b32_e32 v13, 32, v6
	v_add_u32_e32 v4, v15, v4
	v_lshlrev_b32_e32 v6, 5, v11
	v_ashrrev_i16_sdwa v17, v151, sext(v2) dst_sel:DWORD dst_unused:UNUSED_PAD src0_sel:DWORD src1_sel:BYTE_0
	v_mul_lo_u32 v2, v3, s11
	s_addc_u32 s27, s15, s49
	s_lshl_b32 s28, s28, 4
	v_and_b32_e32 v16, 32, v6
	v_or_b32_e32 v2, v2, v13
	v_mul_lo_u32 v3, v4, s11
	v_or_b32_e32 v3, v3, v16
	s_and_b32 s34, s28, 0xfffffc00
	v_add_u32_sdwa v130, v2, sext(v14) dst_sel:DWORD dst_unused:UNUSED_PAD src0_sel:DWORD src1_sel:WORD_0
	v_add_u32_sdwa v132, v3, sext(v17) dst_sel:DWORD dst_unused:UNUSED_PAD src0_sel:DWORD src1_sel:WORD_0
	v_lshlrev_b64 v[18:19], 1, v[130:131]
	s_add_i32 s35, s34, 0x10000
	v_mov_b32_e32 v133, v131
	v_lshl_add_u64 v[2:3], s[26:27], 0, v[18:19]
	s_mov_b32 m0, s35
	v_lshlrev_b64 v[20:21], 1, v[132:133]
	s_add_i32 s36, s34, 0x12000
	global_load_lds_dwordx4 v[2:3], off
	v_lshl_add_u64 v[6:7], s[26:27], 0, v[20:21]
	s_mov_b32 m0, s36
	s_add_i32 s37, s34, 0x2000
	global_load_lds_dwordx4 v[6:7], off
	v_lshl_add_u64 v[8:9], s[22:23], 0, v[18:19]
	s_mov_b32 m0, s34
	s_add_u32 s28, s26, 0xb0000
	global_load_lds_dwordx4 v[8:9], off
	v_lshl_add_u64 v[4:5], s[22:23], 0, v[20:21]
	s_mov_b32 m0, s37
	s_addc_u32 s29, s27, 0
	s_add_i32 s38, s34, 0x14000
	global_load_lds_dwordx4 v[4:5], off
	v_lshl_add_u64 v[22:23], s[28:29], 0, v[18:19]
	s_mov_b32 m0, s38
	s_add_i32 s39, s34, 0x16000
	global_load_lds_dwordx4 v[22:23], off
	v_lshl_add_u64 v[22:23], s[28:29], 0, v[20:21]
	s_add_u32 s28, s22, 0xb0000
	s_mov_b32 m0, s39
	s_addc_u32 s29, s23, 0
	s_add_i32 s40, s34, 0x4000
	global_load_lds_dwordx4 v[22:23], off
	v_lshl_add_u64 v[18:19], s[28:29], 0, v[18:19]
	s_mov_b32 m0, s40
	s_add_i32 s41, s34, 0x6000
	global_load_lds_dwordx4 v[18:19], off
	v_lshl_add_u64 v[18:19], s[28:29], 0, v[20:21]
	s_mov_b32 m0, s41
	s_nop 0
	global_load_lds_dwordx4 v[18:19], off
	s_and_saveexec_b64 s[28:29], vcc
	s_cbranch_execz .LBB0_397
	s_barrier
